# GEMM K-loops: loop-carried SALU moved above the loop-back barrier; FFN1 loop head issues its LDS fragment reads before the pointer-select SALU
# baseline (speedup 1.0000x reference)
; #define PG8_STAGE(bufoff, gbase, voff) do { _Pragma("unroll") for (int _i = 0; _i < 2; ++_i) \
;         __builtin_amdgcn_global_load_lds((const unsigned*)((const char*)(gbase) + (voff)[_i]), (PG8_LAS unsigned*)(lds + (bufoff) + ldsw + _i * 8192), 16, 0, 0); } while (0)
; #define PG8_LDA(dst, b, h) do { _Pragma("unroll") for (int m = 0; m < 4; ++m) _Pragma("unroll") for (int k = 0; k < 2; ++k) dst[m][k] = *(const PG8_LAS bf16x8*)(lds + PG8_SA(b, h) + aoff + m * 2048 + k * 1024); } while (0)
; #define PG8_LDB(dst, b, h) do { _Pragma("unroll") for (int n = 0; n < 2; ++n) _Pragma("unroll") for (int k = 0; k < 2; ++k) dst[n][k] = *(const PG8_LAS bf16x8*)(lds + PG8_SB(b, h) + boff + n * 2048 + k * 1024); } while (0)
; #define PG8_MMA(ai, bj, At, Bt) do { __builtin_amdgcn_s_setprio(1); _Pragma("unroll") for (int m = 0; m < 4; ++m) _Pragma("unroll") for (int n = 0; n < 2; ++n) _Pragma("unroll") for (int k = 0; k < 2; ++k) \
;         acc[ai][bj][m][n] = __builtin_amdgcn_mfma_f32_16x16x32_bf16(Bt[n][k], At[m][k], acc[ai][bj][m][n], 0, 0, 0); __builtin_amdgcn_s_setprio(0); } while (0)
; #define PG8_BAR __builtin_amdgcn_s_barrier()
; template <class Epi, class Sched, bool ALIGN_EPI = false, bool SP2 = false>
; __device__ __forceinline__ void gemm_phase(PG8_LAS unsigned char* lds, const Gemm g, const Sched& S, const Epi& E) {
;     ...
;         const bool has_next = S.next(ui + 1, nxt);
;         const char* nA = has_next ? (const char*)g.A + (size_t)nxt.pm * tstep : cA; const char* nB = has_next ? (const char*)g.Bt + (size_t)nxt.pn * tstep : cB;
;         for (int t = 0; t < nt; t += 2) {
;             const bool last = (t == nt - 2);
;             const char* a1 = cA + (size_t)(t + 1) * kstep;
;             const char* a2 = last ? nA : cA + (size_t)(t + 2) * kstep; const char* b2 = last ? nB : cB + (size_t)(t + 2) * kstep;
;             const char* a3 = a2 + kstep; const char* b3 = b2 + kstep;
;             if (last && has_next) S.a_ready(nxt);
;             if constexpr (SP2) {
;             PG8_LDB(B0, 0, 0); PG8_LDB(B1, 0, 1); PG8_SCHED; PG8_LDA(At, 0, 0); PG8_STAGE(PG8_SA(1, 1), a1 + hstep, voffA);
;             PG8_WAIT_V(8); PG8_WAIT_L(0); PG8_BAR; PG8_MMA(0, 0, At, B0); PG8_MMA(0, 1, At, B1); PG8_BAR; PG8_SCHED;
;             PG8_LDA(At, 0, 1); PG8_STAGE(PG8_SB(0, 0), b2, voffB); PG8_STAGE(PG8_SB(0, 1), b2 + hstep, voffB); PG8_STAGE(PG8_SA(0, 0), a2, voffA);
.LBB0_106:
	s_add_i32 s58, 0, 0x10000
	s_add_i32 s59, 0, 0x14000
	v_add_u32_e32 v144, s58, v152
	ds_read_b128 v[140:143], v144
	ds_read_b128 v[148:151], v144 offset:1024
	ds_read_b128 v[156:159], v144 offset:2048
	ds_read_b128 v[174:177], v144 offset:3072
	v_add_u32_e32 v144, s59, v152
	ds_read_b128 v[178:181], v144
	ds_read_b128 v[182:185], v144 offset:1024
	ds_read_b128 v[186:189], v144 offset:2048
	ds_read_b128 v[190:193], v144 offset:3072
	s_add_i32 s55, s22, 2
	s_add_u32 s56, s20, 0x80
	s_addc_u32 s23, s21, 0
	s_cmp_eq_u32 s46, s22
	s_cselect_b32 s23, s3, s23
	s_cselect_b32 s22, s2, s56
	s_cselect_b32 s57, s19, s54
	s_cselect_b32 s56, s18, s53
	v_lshl_add_u64 v[144:145], s[20:21], 0, v[138:139]
	s_add_i32 m0, s39, 0xc000
	ds_read_b128 v[194:197], v155
	ds_read_b128 v[198:201], v155 offset:1024
	ds_read_b128 v[202:205], v155 offset:2048
	ds_read_b128 v[206:209], v155 offset:3072
	ds_read_b128 v[210:213], v155 offset:4096
	ds_read_b128 v[214:217], v155 offset:5120
	ds_read_b128 v[218:221], v155 offset:6144
	ds_read_b128 v[222:225], v155 offset:7168
	global_load_lds_dwordx4 v[144:145], off
	v_lshl_add_u64 v[144:145], s[20:21], 0, v[136:137]
	s_add_i32 m0, s39, 0xe000
	s_nop 0
	global_load_lds_dwordx4 v[144:145], off
	s_waitcnt vmcnt(8)
	s_waitcnt lgkmcnt(0)
	s_barrier
	s_setprio 1
	s_waitcnt lgkmcnt(0)
	v_mfma_f32_16x16x32_bf16 v[122:125], v[140:143], v[194:197], v[122:125]
	v_mfma_f32_16x16x32_bf16 v[114:117], v[156:159], v[194:197], v[114:117]
	v_mfma_f32_16x16x32_bf16 v[106:109], v[140:143], v[202:205], v[106:109]
	v_mfma_f32_16x16x32_bf16 v[98:101], v[156:159], v[202:205], v[98:101]
	v_mfma_f32_16x16x32_bf16 v[90:93], v[140:143], v[210:213], v[90:93]
	v_mfma_f32_16x16x32_bf16 v[82:85], v[156:159], v[210:213], v[82:85]
	v_mfma_f32_16x16x32_bf16 v[74:77], v[140:143], v[218:221], v[74:77]
	v_mfma_f32_16x16x32_bf16 v[66:69], v[156:159], v[218:221], v[66:69]
	v_mfma_f32_16x16x32_bf16 v[122:125], v[148:151], v[198:201], v[122:125]
	v_mfma_f32_16x16x32_bf16 v[114:117], v[174:177], v[198:201], v[114:117]
	v_mfma_f32_16x16x32_bf16 v[106:109], v[148:151], v[206:209], v[106:109]
	v_mfma_f32_16x16x32_bf16 v[98:101], v[174:177], v[206:209], v[98:101]
	v_mfma_f32_16x16x32_bf16 v[90:93], v[148:151], v[214:217], v[90:93]
	v_mfma_f32_16x16x32_bf16 v[82:85], v[174:177], v[214:217], v[82:85]
	v_mfma_f32_16x16x32_bf16 v[74:77], v[148:151], v[222:225], v[74:77]
	v_mfma_f32_16x16x32_bf16 v[66:69], v[174:177], v[222:225], v[66:69]
	s_setprio 0
	s_setprio 1
	v_mfma_f32_16x16x32_bf16 v[126:129], v[178:181], v[194:197], v[126:129]
	v_mfma_f32_16x16x32_bf16 v[118:121], v[186:189], v[194:197], v[118:121]
	v_mfma_f32_16x16x32_bf16 v[110:113], v[178:181], v[202:205], v[110:113]
	v_mfma_f32_16x16x32_bf16 v[102:105], v[186:189], v[202:205], v[102:105]
	v_mfma_f32_16x16x32_bf16 v[94:97], v[178:181], v[210:213], v[94:97]
	v_mfma_f32_16x16x32_bf16 v[86:89], v[186:189], v[210:213], v[86:89]
	v_mfma_f32_16x16x32_bf16 v[78:81], v[178:181], v[218:221], v[78:81]
	v_mfma_f32_16x16x32_bf16 v[70:73], v[186:189], v[218:221], v[70:73]
	v_mfma_f32_16x16x32_bf16 v[126:129], v[182:185], v[198:201], v[126:129]
	v_mfma_f32_16x16x32_bf16 v[118:121], v[190:193], v[198:201], v[118:121]
	v_mfma_f32_16x16x32_bf16 v[110:113], v[182:185], v[206:209], v[110:113]
	v_mfma_f32_16x16x32_bf16 v[102:105], v[190:193], v[206:209], v[102:105]
	v_mfma_f32_16x16x32_bf16 v[94:97], v[182:185], v[214:217], v[94:97]
	v_mfma_f32_16x16x32_bf16 v[86:89], v[190:193], v[214:217], v[86:89]
	v_mfma_f32_16x16x32_bf16 v[78:81], v[182:185], v[222:225], v[78:81]
	v_mfma_f32_16x16x32_bf16 v[70:73], v[190:193], v[222:225], v[70:73]
	s_setprio 0
	s_barrier
	s_add_i32 s58, s58, s25
	v_lshl_add_u64 v[144:145], s[56:57], 0, v[0:1]
	s_mov_b32 m0, s58
	ds_read_b128 v[194:197], v155 offset:16384
	ds_read_b128 v[198:201], v155 offset:17408
	ds_read_b128 v[202:205], v155 offset:18432
	ds_read_b128 v[206:209], v155 offset:19456
	ds_read_b128 v[210:213], v155 offset:20480
	ds_read_b128 v[214:217], v155 offset:21504
	ds_read_b128 v[218:221], v155 offset:22528
	ds_read_b128 v[222:225], v155 offset:23552
	global_load_lds_dwordx4 v[144:145], off
	s_add_i32 m0, s58, 0x2000
	v_lshl_add_u64 v[160:161], s[56:57], 0, v[130:131]
	s_add_u32 s56, s56, s6
	s_addc_u32 s57, s57, s7
	s_add_i32 s58, s59, s25
	global_load_lds_dwordx4 v[160:161], off
	v_lshl_add_u64 v[226:227], s[56:57], 0, v[0:1]
	s_mov_b32 m0, s58
	v_lshl_add_u64 v[228:229], s[56:57], 0, v[130:131]
	global_load_lds_dwordx4 v[226:227], off
	s_add_i32 m0, s58, 0x2000
	v_lshl_add_u64 v[230:231], s[22:23], 0, v[134:135]
	global_load_lds_dwordx4 v[228:229], off
	s_mov_b32 m0, s39
	v_lshl_add_u64 v[232:233], s[22:23], 0, v[132:133]
	global_load_lds_dwordx4 v[230:231], off
	s_mov_b32 m0, s40
	s_nop 0
	global_load_lds_dwordx4 v[232:233], off
	s_waitcnt vmcnt(8)
	s_waitcnt lgkmcnt(0)
	s_barrier
; #define PG8_STAGE(bufoff, gbase, voff) do { _Pragma("unroll") for (int _i = 0; _i < 2; ++_i) \
;         __builtin_amdgcn_global_load_lds((const unsigned*)((const char*)(gbase) + (voff)[_i]), (PG8_LAS unsigned*)(lds + (bufoff) + ldsw + _i * 8192), 16, 0, 0); } while (0)
; #define PG8_LDA(dst, b, h) do { _Pragma("unroll") for (int m = 0; m < 4; ++m) _Pragma("unroll") for (int k = 0; k < 2; ++k) dst[m][k] = *(const PG8_LAS bf16x8*)(lds + PG8_SA(b, h) + aoff + m * 2048 + k * 1024); } while (0)
; #define PG8_LDB(dst, b, h) do { _Pragma("unroll") for (int n = 0; n < 2; ++n) _Pragma("unroll") for (int k = 0; k < 2; ++k) dst[n][k] = *(const PG8_LAS bf16x8*)(lds + PG8_SB(b, h) + boff + n * 2048 + k * 1024); } while (0)
; #define PG8_MMA(ai, bj, At, Bt) do { __builtin_amdgcn_s_setprio(1); _Pragma("unroll") for (int m = 0; m < 4; ++m) _Pragma("unroll") for (int n = 0; n < 2; ++n) _Pragma("unroll") for (int k = 0; k < 2; ++k) \
;         acc[ai][bj][m][n] = __builtin_amdgcn_mfma_f32_16x16x32_bf16(Bt[n][k], At[m][k], acc[ai][bj][m][n], 0, 0, 0); __builtin_amdgcn_s_setprio(0); } while (0)
; #define PG8_WAIT_V(n) asm volatile("s_waitcnt vmcnt(" #n ")" ::: "memory")
; #define PG8_WAIT_L(n) asm volatile("s_waitcnt lgkmcnt(" #n ")" ::: "memory")
; #define PG8_BAR __builtin_amdgcn_s_barrier()
; #define PG8_SCHED __builtin_amdgcn_sched_barrier(0)
; template <class Epi, class Sched, bool ALIGN_EPI = false, bool SP2 = false>
; __device__ __forceinline__ void gemm_phase(PG8_LAS unsigned char* lds, const Gemm g, const Sched& S, const Epi& E) {
;     ...
;             PG8_WAIT_V(8); PG8_WAIT_L(0); PG8_BAR; PG8_MMA(1, 0, At, B0); PG8_MMA(1, 1, At, B1); PG8_BAR; PG8_SCHED;
;             PG8_LDB(B0, 1, 0); PG8_LDB(B1, 1, 1); PG8_SCHED; PG8_LDA(At, 1, 0); PG8_STAGE(PG8_SA(0, 1), a2 + hstep, voffA);
;             PG8_WAIT_V(8); PG8_WAIT_L(0); PG8_BAR; PG8_MMA(0, 0, At, B0); PG8_MMA(0, 1, At, B1); PG8_BAR; PG8_SCHED;
	s_setprio 1
	s_waitcnt lgkmcnt(0)
	v_mfma_f32_16x16x32_bf16 v[58:61], v[140:143], v[194:197], v[58:61]
	v_mfma_f32_16x16x32_bf16 v[50:53], v[156:159], v[194:197], v[50:53]
	v_mfma_f32_16x16x32_bf16 v[42:45], v[140:143], v[202:205], v[42:45]
	v_mfma_f32_16x16x32_bf16 v[34:37], v[156:159], v[202:205], v[34:37]
	v_mfma_f32_16x16x32_bf16 v[26:29], v[140:143], v[210:213], v[26:29]
	v_mfma_f32_16x16x32_bf16 v[18:21], v[156:159], v[210:213], v[18:21]
	v_mfma_f32_16x16x32_bf16 v[10:13], v[140:143], v[218:221], v[10:13]
	v_mfma_f32_16x16x32_bf16 v[6:9], v[156:159], v[218:221], v[6:9]
	v_mfma_f32_16x16x32_bf16 v[58:61], v[148:151], v[198:201], v[58:61]
	v_mfma_f32_16x16x32_bf16 v[50:53], v[174:177], v[198:201], v[50:53]
	v_mfma_f32_16x16x32_bf16 v[42:45], v[148:151], v[206:209], v[42:45]
	v_mfma_f32_16x16x32_bf16 v[34:37], v[174:177], v[206:209], v[34:37]
	v_mfma_f32_16x16x32_bf16 v[26:29], v[148:151], v[214:217], v[26:29]
	v_mfma_f32_16x16x32_bf16 v[18:21], v[174:177], v[214:217], v[18:21]
	v_mfma_f32_16x16x32_bf16 v[10:13], v[148:151], v[222:225], v[10:13]
	v_mfma_f32_16x16x32_bf16 v[6:9], v[174:177], v[222:225], v[6:9]
	s_setprio 0
	s_setprio 1
	v_mfma_f32_16x16x32_bf16 v[62:65], v[178:181], v[194:197], v[62:65]
	v_mfma_f32_16x16x32_bf16 v[54:57], v[186:189], v[194:197], v[54:57]
	v_mfma_f32_16x16x32_bf16 v[46:49], v[178:181], v[202:205], v[46:49]
	v_mfma_f32_16x16x32_bf16 v[38:41], v[186:189], v[202:205], v[38:41]
	v_mfma_f32_16x16x32_bf16 v[30:33], v[178:181], v[210:213], v[30:33]
	v_mfma_f32_16x16x32_bf16 v[22:25], v[186:189], v[210:213], v[22:25]
	v_mfma_f32_16x16x32_bf16 v[14:17], v[178:181], v[218:221], v[14:17]
	v_mfma_f32_16x16x32_bf16 v[2:5], v[186:189], v[218:221], v[2:5]
	v_mfma_f32_16x16x32_bf16 v[62:65], v[182:185], v[198:201], v[62:65]
	v_mfma_f32_16x16x32_bf16 v[54:57], v[190:193], v[198:201], v[54:57]
	v_mfma_f32_16x16x32_bf16 v[46:49], v[182:185], v[206:209], v[46:49]
	v_mfma_f32_16x16x32_bf16 v[38:41], v[190:193], v[206:209], v[38:41]
	v_mfma_f32_16x16x32_bf16 v[30:33], v[182:185], v[214:217], v[30:33]
	v_mfma_f32_16x16x32_bf16 v[22:25], v[190:193], v[214:217], v[22:25]
	v_mfma_f32_16x16x32_bf16 v[14:17], v[182:185], v[222:225], v[14:17]
	v_mfma_f32_16x16x32_bf16 v[2:5], v[190:193], v[222:225], v[2:5]
	s_setprio 0
	s_barrier
	s_add_i32 s56, 0, 0x18000
	s_add_i32 s57, 0, 0x1c000
	v_add_u32_e32 v174, s56, v152
	v_add_u32_e32 v190, s57, v152
	ds_read_b128 v[140:143], v174
	ds_read_b128 v[148:151], v174 offset:1024
	ds_read_b128 v[156:159], v174 offset:2048
	ds_read_b128 v[174:177], v174 offset:3072
	ds_read_b128 v[178:181], v190
	ds_read_b128 v[182:185], v190 offset:1024
	ds_read_b128 v[186:189], v190 offset:2048
	ds_read_b128 v[190:193], v190 offset:3072
	s_add_u32 s22, s22, s6
	s_addc_u32 s23, s23, s7
	s_mov_b32 m0, s41
	v_lshl_add_u64 v[234:235], s[22:23], 0, v[134:135]
	ds_read_b128 v[194:197], v155 offset:32768
	ds_read_b128 v[198:201], v155 offset:33792
	ds_read_b128 v[202:205], v155 offset:34816
	ds_read_b128 v[206:209], v155 offset:35840
	ds_read_b128 v[210:213], v155 offset:36864
	ds_read_b128 v[214:217], v155 offset:37888
	ds_read_b128 v[218:221], v155 offset:38912
	ds_read_b128 v[222:225], v155 offset:39936
	global_load_lds_dwordx4 v[234:235], off
	v_lshl_add_u64 v[234:235], s[22:23], 0, v[132:133]
	s_mov_b32 m0, s42
	s_nop 0
	global_load_lds_dwordx4 v[234:235], off
	s_waitcnt vmcnt(8)
	s_waitcnt lgkmcnt(0)
	s_barrier
	s_setprio 1
	s_waitcnt lgkmcnt(0)
	v_mfma_f32_16x16x32_bf16 v[122:125], v[140:143], v[194:197], v[122:125]
	v_mfma_f32_16x16x32_bf16 v[114:117], v[156:159], v[194:197], v[114:117]
	v_mfma_f32_16x16x32_bf16 v[106:109], v[140:143], v[202:205], v[106:109]
	v_mfma_f32_16x16x32_bf16 v[98:101], v[156:159], v[202:205], v[98:101]
	v_mfma_f32_16x16x32_bf16 v[90:93], v[140:143], v[210:213], v[90:93]
	v_mfma_f32_16x16x32_bf16 v[82:85], v[156:159], v[210:213], v[82:85]
	v_mfma_f32_16x16x32_bf16 v[74:77], v[140:143], v[218:221], v[74:77]
	v_mfma_f32_16x16x32_bf16 v[66:69], v[156:159], v[218:221], v[66:69]
	v_mfma_f32_16x16x32_bf16 v[122:125], v[148:151], v[198:201], v[122:125]
	v_mfma_f32_16x16x32_bf16 v[114:117], v[174:177], v[198:201], v[114:117]
	v_mfma_f32_16x16x32_bf16 v[106:109], v[148:151], v[206:209], v[106:109]
	v_mfma_f32_16x16x32_bf16 v[98:101], v[174:177], v[206:209], v[98:101]
	v_mfma_f32_16x16x32_bf16 v[90:93], v[148:151], v[214:217], v[90:93]
	v_mfma_f32_16x16x32_bf16 v[82:85], v[174:177], v[214:217], v[82:85]
	v_mfma_f32_16x16x32_bf16 v[74:77], v[148:151], v[222:225], v[74:77]
	v_mfma_f32_16x16x32_bf16 v[66:69], v[174:177], v[222:225], v[66:69]
	s_setprio 0
	s_setprio 1
	v_mfma_f32_16x16x32_bf16 v[126:129], v[178:181], v[194:197], v[126:129]
	v_mfma_f32_16x16x32_bf16 v[118:121], v[186:189], v[194:197], v[118:121]
	v_mfma_f32_16x16x32_bf16 v[110:113], v[178:181], v[202:205], v[110:113]
	v_mfma_f32_16x16x32_bf16 v[102:105], v[186:189], v[202:205], v[102:105]
	v_mfma_f32_16x16x32_bf16 v[94:97], v[178:181], v[210:213], v[94:97]
	v_mfma_f32_16x16x32_bf16 v[86:89], v[186:189], v[210:213], v[86:89]
	v_mfma_f32_16x16x32_bf16 v[78:81], v[178:181], v[218:221], v[78:81]
	v_mfma_f32_16x16x32_bf16 v[70:73], v[186:189], v[218:221], v[70:73]
	v_mfma_f32_16x16x32_bf16 v[126:129], v[182:185], v[198:201], v[126:129]
	v_mfma_f32_16x16x32_bf16 v[118:121], v[190:193], v[198:201], v[118:121]
	v_mfma_f32_16x16x32_bf16 v[110:113], v[182:185], v[206:209], v[110:113]
	v_mfma_f32_16x16x32_bf16 v[102:105], v[190:193], v[206:209], v[102:105]
	v_mfma_f32_16x16x32_bf16 v[94:97], v[182:185], v[214:217], v[94:97]
	v_mfma_f32_16x16x32_bf16 v[86:89], v[190:193], v[214:217], v[86:89]
	v_mfma_f32_16x16x32_bf16 v[78:81], v[182:185], v[222:225], v[78:81]
	v_mfma_f32_16x16x32_bf16 v[70:73], v[190:193], v[222:225], v[70:73]
	s_setprio 0
	s_barrier
; #define PG8_STAGE(bufoff, gbase, voff) do { _Pragma("unroll") for (int _i = 0; _i < 2; ++_i) \
;         __builtin_amdgcn_global_load_lds((const unsigned*)((const char*)(gbase) + (voff)[_i]), (PG8_LAS unsigned*)(lds + (bufoff) + ldsw + _i * 8192), 16, 0, 0); } while (0)
; #define PG8_LDA(dst, b, h) do { _Pragma("unroll") for (int m = 0; m < 4; ++m) _Pragma("unroll") for (int k = 0; k < 2; ++k) dst[m][k] = *(const PG8_LAS bf16x8*)(lds + PG8_SA(b, h) + aoff + m * 2048 + k * 1024); } while (0)
; #define PG8_MMA(ai, bj, At, Bt) do { __builtin_amdgcn_s_setprio(1); _Pragma("unroll") for (int m = 0; m < 4; ++m) _Pragma("unroll") for (int n = 0; n < 2; ++n) _Pragma("unroll") for (int k = 0; k < 2; ++k) \
;         acc[ai][bj][m][n] = __builtin_amdgcn_mfma_f32_16x16x32_bf16(Bt[n][k], At[m][k], acc[ai][bj][m][n], 0, 0, 0); __builtin_amdgcn_s_setprio(0); } while (0)
; #define PG8_WAIT_V(n) asm volatile("s_waitcnt vmcnt(" #n ")" ::: "memory")
; #define PG8_WAIT_L(n) asm volatile("s_waitcnt lgkmcnt(" #n ")" ::: "memory")
; #define PG8_BAR __builtin_amdgcn_s_barrier()
; #define PG8_SCHED __builtin_amdgcn_sched_barrier(0)
; template <class Epi, class Sched, bool ALIGN_EPI = false, bool SP2 = false>
; __device__ __forceinline__ void gemm_phase(PG8_LAS unsigned char* lds, const Gemm g, const Sched& S, const Epi& E) {
;     ...
;         for (int t = 0; t < nt; t += 2) {
;     ...
;             PG8_LDA(At, 1, 1); PG8_STAGE(PG8_SB(1, 0), b3, voffB); PG8_STAGE(PG8_SB(1, 1), b3 + hstep, voffB); PG8_STAGE(PG8_SA(1, 0), a3, voffA);
;             PG8_WAIT_V(8); PG8_WAIT_L(0); PG8_BAR; PG8_MMA(1, 0, At, B0); PG8_MMA(1, 1, At, B1); PG8_BAR; PG8_SCHED;
	s_add_i32 s22, s56, s25
	v_lshl_add_u64 v[144:145], v[144:145], 0, s[80:81]
	s_mov_b32 m0, s22
	ds_read_b128 v[194:197], v155 offset:49152
	ds_read_b128 v[198:201], v155 offset:50176
	ds_read_b128 v[202:205], v155 offset:51200
	ds_read_b128 v[206:209], v155 offset:52224
	ds_read_b128 v[210:213], v155 offset:53248
	ds_read_b128 v[214:217], v155 offset:54272
	ds_read_b128 v[218:221], v155 offset:55296
	ds_read_b128 v[222:225], v155 offset:56320
	global_load_lds_dwordx4 v[144:145], off
	v_lshl_add_u64 v[144:145], v[160:161], 0, s[80:81]
	s_add_i32 m0, s22, 0x2000
	s_add_i32 s22, s57, s25
	global_load_lds_dwordx4 v[144:145], off
	v_lshl_add_u64 v[144:145], v[226:227], 0, s[80:81]
	s_mov_b32 m0, s22
	s_nop 0
	global_load_lds_dwordx4 v[144:145], off
	v_lshl_add_u64 v[144:145], v[228:229], 0, s[80:81]
	s_add_i32 m0, s22, 0x2000
	s_nop 0
	global_load_lds_dwordx4 v[144:145], off
	v_lshl_add_u64 v[144:145], v[230:231], 0, s[80:81]
	s_mov_b32 m0, s44
	s_nop 0
	global_load_lds_dwordx4 v[144:145], off
	v_lshl_add_u64 v[144:145], v[232:233], 0, s[80:81]
	s_mov_b32 m0, s45
	s_nop 0
	global_load_lds_dwordx4 v[144:145], off
	s_waitcnt vmcnt(8)
	s_waitcnt lgkmcnt(0)
	s_barrier
	s_setprio 1
	s_waitcnt lgkmcnt(0)
	v_mfma_f32_16x16x32_bf16 v[58:61], v[140:143], v[194:197], v[58:61]
	v_mfma_f32_16x16x32_bf16 v[50:53], v[156:159], v[194:197], v[50:53]
	v_mfma_f32_16x16x32_bf16 v[42:45], v[140:143], v[202:205], v[42:45]
	v_mfma_f32_16x16x32_bf16 v[34:37], v[156:159], v[202:205], v[34:37]
	v_mfma_f32_16x16x32_bf16 v[26:29], v[140:143], v[210:213], v[26:29]
	v_mfma_f32_16x16x32_bf16 v[18:21], v[156:159], v[210:213], v[18:21]
	v_mfma_f32_16x16x32_bf16 v[10:13], v[140:143], v[218:221], v[10:13]
	v_mfma_f32_16x16x32_bf16 v[6:9], v[156:159], v[218:221], v[6:9]
	v_mfma_f32_16x16x32_bf16 v[58:61], v[148:151], v[198:201], v[58:61]
	v_mfma_f32_16x16x32_bf16 v[50:53], v[174:177], v[198:201], v[50:53]
	v_mfma_f32_16x16x32_bf16 v[42:45], v[148:151], v[206:209], v[42:45]
	v_mfma_f32_16x16x32_bf16 v[34:37], v[174:177], v[206:209], v[34:37]
	v_mfma_f32_16x16x32_bf16 v[26:29], v[148:151], v[214:217], v[26:29]
	v_mfma_f32_16x16x32_bf16 v[18:21], v[174:177], v[214:217], v[18:21]
	v_mfma_f32_16x16x32_bf16 v[10:13], v[148:151], v[222:225], v[10:13]
	v_mfma_f32_16x16x32_bf16 v[6:9], v[174:177], v[222:225], v[6:9]
	s_setprio 0
	s_setprio 1
	v_mfma_f32_16x16x32_bf16 v[62:65], v[178:181], v[194:197], v[62:65]
	v_mfma_f32_16x16x32_bf16 v[54:57], v[186:189], v[194:197], v[54:57]
	v_mfma_f32_16x16x32_bf16 v[46:49], v[178:181], v[202:205], v[46:49]
	v_mfma_f32_16x16x32_bf16 v[38:41], v[186:189], v[202:205], v[38:41]
	v_mfma_f32_16x16x32_bf16 v[30:33], v[178:181], v[210:213], v[30:33]
	v_mfma_f32_16x16x32_bf16 v[22:25], v[186:189], v[210:213], v[22:25]
	v_mfma_f32_16x16x32_bf16 v[14:17], v[178:181], v[218:221], v[14:17]
	v_mfma_f32_16x16x32_bf16 v[2:5], v[186:189], v[218:221], v[2:5]
	v_mfma_f32_16x16x32_bf16 v[62:65], v[182:185], v[198:201], v[62:65]
	v_mfma_f32_16x16x32_bf16 v[54:57], v[190:193], v[198:201], v[54:57]
	v_mfma_f32_16x16x32_bf16 v[46:49], v[182:185], v[206:209], v[46:49]
	v_mfma_f32_16x16x32_bf16 v[38:41], v[190:193], v[206:209], v[38:41]
	v_mfma_f32_16x16x32_bf16 v[30:33], v[182:185], v[214:217], v[30:33]
	v_mfma_f32_16x16x32_bf16 v[22:25], v[190:193], v[214:217], v[22:25]
	v_mfma_f32_16x16x32_bf16 v[14:17], v[182:185], v[222:225], v[14:17]
	v_mfma_f32_16x16x32_bf16 v[2:5], v[190:193], v[222:225], v[2:5]
	s_setprio 0
	s_add_u32 s53, s53, 0x100
	s_addc_u32 s54, s54, 0
	s_add_u32 s20, s20, 0x100
	s_addc_u32 s21, s21, 0
	s_cmp_ge_i32 s55, s43
	s_mov_b32 s22, s55
	s_barrier
	s_cbranch_scc0 .LBB0_106
	v_readlane_b32 s56, v239, 36
	v_readlane_b32 s57, v239, 37

; #define PG8_STAGE(bufoff, gbase, voff) do { _Pragma("unroll") for (int _i = 0; _i < 2; ++_i) \
;         __builtin_amdgcn_global_load_lds((const unsigned*)((const char*)(gbase) + (voff)[_i]), (PG8_LAS unsigned*)(lds + (bufoff) + ldsw + _i * 8192), 16, 0, 0); } while (0)
; #define PG8_LDA(dst, b, h) do { _Pragma("unroll") for (int m = 0; m < 4; ++m) _Pragma("unroll") for (int k = 0; k < 2; ++k) dst[m][k] = *(const PG8_LAS bf16x8*)(lds + PG8_SA(b, h) + aoff + m * 2048 + k * 1024); } while (0)
; #define PG8_LDB(dst, b, h) do { _Pragma("unroll") for (int n = 0; n < 2; ++n) _Pragma("unroll") for (int k = 0; k < 2; ++k) dst[n][k] = *(const PG8_LAS bf16x8*)(lds + PG8_SB(b, h) + boff + n * 2048 + k * 1024); } while (0)
; #define PG8_MMA(ai, bj, At, Bt) do { __builtin_amdgcn_s_setprio(1); _Pragma("unroll") for (int m = 0; m < 4; ++m) _Pragma("unroll") for (int n = 0; n < 2; ++n) _Pragma("unroll") for (int k = 0; k < 2; ++k) \
;         acc[ai][bj][m][n] = __builtin_amdgcn_mfma_f32_16x16x32_bf16(Bt[n][k], At[m][k], acc[ai][bj][m][n], 0, 0, 0); __builtin_amdgcn_s_setprio(0); } while (0)
; #define PG8_WAIT_V(n) asm volatile("s_waitcnt vmcnt(" #n ")" ::: "memory")
; #define PG8_WAIT_L(n) asm volatile("s_waitcnt lgkmcnt(" #n ")" ::: "memory")
; #define PG8_BAR __builtin_amdgcn_s_barrier()
; #define PG8_SCHED __builtin_amdgcn_sched_barrier(0)
; template <class Epi, class Sched, bool ALIGN_EPI = false, bool SP2 = false>
; __device__ __forceinline__ void gemm_phase(PG8_LAS unsigned char* lds, const Gemm g, const Sched& S, const Epi& E) {
;     ...
;             const bool last = (t == nt - 2);
;             const char* a1 = cA + (size_t)(t + 1) * kstep;
;             const char* a2 = last ? nA : cA + (size_t)(t + 2) * kstep; const char* b2 = last ? nB : cB + (size_t)(t + 2) * kstep;
;             const char* a3 = a2 + kstep; const char* b3 = b2 + kstep;
;             if (last && has_next) S.a_ready(nxt);
;             if constexpr (SP2) {
;             PG8_LDB(B0, 0, 0); PG8_LDB(B1, 0, 1); PG8_SCHED; PG8_LDA(At, 0, 0); PG8_STAGE(PG8_SA(1, 1), a1 + hstep, voffA);
;             PG8_WAIT_V(8); PG8_WAIT_L(0); PG8_BAR; PG8_MMA(0, 0, At, B0); PG8_MMA(0, 1, At, B1); PG8_BAR; PG8_SCHED;
;             PG8_LDA(At, 0, 1); PG8_STAGE(PG8_SB(0, 0), b2, voffB); PG8_STAGE(PG8_SB(0, 1), b2 + hstep, voffB); PG8_STAGE(PG8_SA(0, 0), a2, voffA);
.LBB0_190:
	s_add_i32 s30, s28, 2
	s_add_u32 s31, s2, 0x80
	s_addc_u32 s29, s3, 0
	s_add_i32 s63, 0, 0x10000
	s_cmp_eq_u32 s54, s28
	s_cselect_b32 s29, s25, s29
	s_cselect_b32 s28, s24, s31
	s_cselect_b32 s65, s27, s62
	s_cselect_b32 s64, s26, s61
	s_add_i32 s31, 0, 0x14000
	v_add_u32_e32 v142, s63, v174
	v_add_u32_e32 v186, s31, v174
	ds_read_b128 v[130:133], v142
	ds_read_b128 v[134:137], v142 offset:1024
	ds_read_b128 v[138:141], v142 offset:2048
	ds_read_b128 v[142:145], v142 offset:3072
	ds_read_b128 v[158:161], v186
	ds_read_b128 v[178:181], v186 offset:1024
	ds_read_b128 v[182:185], v186 offset:2048
	ds_read_b128 v[186:189], v186 offset:3072
	v_lshl_add_u64 v[222:223], s[2:3], 0, v[156:157]
	s_add_i32 m0, s47, 0xc000
	ds_read_b128 v[190:193], v177
	ds_read_b128 v[194:197], v177 offset:1024
	ds_read_b128 v[198:201], v177 offset:2048
	ds_read_b128 v[202:205], v177 offset:3072
	ds_read_b128 v[206:209], v177 offset:4096
	ds_read_b128 v[210:213], v177 offset:5120
	ds_read_b128 v[214:217], v177 offset:6144
	ds_read_b128 v[218:221], v177 offset:7168
	global_load_lds_dwordx4 v[222:223], off
	v_lshl_add_u64 v[222:223], s[2:3], 0, v[154:155]
	s_add_i32 m0, s47, 0xe000
	s_nop 0
	global_load_lds_dwordx4 v[222:223], off
	s_waitcnt vmcnt(8)
	s_waitcnt lgkmcnt(0)
	s_barrier
	s_setprio 1
	s_waitcnt lgkmcnt(0)
	v_mfma_f32_16x16x32_bf16 v[126:129], v[130:133], v[190:193], v[126:129]
	v_mfma_f32_16x16x32_bf16 v[122:125], v[138:141], v[190:193], v[122:125]
	v_mfma_f32_16x16x32_bf16 v[110:113], v[130:133], v[198:201], v[110:113]
	v_mfma_f32_16x16x32_bf16 v[106:109], v[138:141], v[198:201], v[106:109]
	v_mfma_f32_16x16x32_bf16 v[94:97], v[130:133], v[206:209], v[94:97]
	v_mfma_f32_16x16x32_bf16 v[90:93], v[138:141], v[206:209], v[90:93]
	v_mfma_f32_16x16x32_bf16 v[78:81], v[130:133], v[214:217], v[78:81]
	v_mfma_f32_16x16x32_bf16 v[74:77], v[138:141], v[214:217], v[74:77]
	v_mfma_f32_16x16x32_bf16 v[126:129], v[134:137], v[194:197], v[126:129]
	v_mfma_f32_16x16x32_bf16 v[122:125], v[142:145], v[194:197], v[122:125]
	v_mfma_f32_16x16x32_bf16 v[110:113], v[134:137], v[202:205], v[110:113]
	v_mfma_f32_16x16x32_bf16 v[106:109], v[142:145], v[202:205], v[106:109]
	v_mfma_f32_16x16x32_bf16 v[94:97], v[134:137], v[210:213], v[94:97]
	v_mfma_f32_16x16x32_bf16 v[90:93], v[142:145], v[210:213], v[90:93]
	v_mfma_f32_16x16x32_bf16 v[78:81], v[134:137], v[218:221], v[78:81]
	v_mfma_f32_16x16x32_bf16 v[74:77], v[142:145], v[218:221], v[74:77]
	s_setprio 0
	s_setprio 1
	v_mfma_f32_16x16x32_bf16 v[118:121], v[158:161], v[190:193], v[118:121]
	v_mfma_f32_16x16x32_bf16 v[114:117], v[182:185], v[190:193], v[114:117]
	v_mfma_f32_16x16x32_bf16 v[102:105], v[158:161], v[198:201], v[102:105]
	v_mfma_f32_16x16x32_bf16 v[98:101], v[182:185], v[198:201], v[98:101]
	v_mfma_f32_16x16x32_bf16 v[86:89], v[158:161], v[206:209], v[86:89]
	v_mfma_f32_16x16x32_bf16 v[82:85], v[182:185], v[206:209], v[82:85]
	v_mfma_f32_16x16x32_bf16 v[70:73], v[158:161], v[214:217], v[70:73]
	v_mfma_f32_16x16x32_bf16 v[66:69], v[182:185], v[214:217], v[66:69]
	v_mfma_f32_16x16x32_bf16 v[118:121], v[178:181], v[194:197], v[118:121]
	v_mfma_f32_16x16x32_bf16 v[114:117], v[186:189], v[194:197], v[114:117]
	v_mfma_f32_16x16x32_bf16 v[102:105], v[178:181], v[202:205], v[102:105]
	v_mfma_f32_16x16x32_bf16 v[98:101], v[186:189], v[202:205], v[98:101]
	v_mfma_f32_16x16x32_bf16 v[86:89], v[178:181], v[210:213], v[86:89]
	v_mfma_f32_16x16x32_bf16 v[82:85], v[186:189], v[210:213], v[82:85]
	v_mfma_f32_16x16x32_bf16 v[70:73], v[178:181], v[218:221], v[70:73]
	v_mfma_f32_16x16x32_bf16 v[66:69], v[186:189], v[218:221], v[66:69]
	s_setprio 0
	s_barrier
	s_add_i32 s63, s63, s36
	v_lshl_add_u64 v[222:223], s[64:65], 0, v[0:1]
	s_mov_b32 m0, s63
	ds_read_b128 v[190:193], v177 offset:16384
	ds_read_b128 v[194:197], v177 offset:17408
	ds_read_b128 v[198:201], v177 offset:18432
	ds_read_b128 v[202:205], v177 offset:19456
	ds_read_b128 v[206:209], v177 offset:20480
	ds_read_b128 v[210:213], v177 offset:21504
	ds_read_b128 v[214:217], v177 offset:22528
	ds_read_b128 v[218:221], v177 offset:23552
	global_load_lds_dwordx4 v[222:223], off
	s_add_i32 m0, s63, 0x2000
	v_lshl_add_u64 v[224:225], s[64:65], 0, v[148:149]
	s_add_u32 s64, s64, s10
	s_addc_u32 s65, s65, s11
	s_add_i32 s31, s31, s36
	global_load_lds_dwordx4 v[224:225], off
	v_lshl_add_u64 v[226:227], s[64:65], 0, v[0:1]
	s_mov_b32 m0, s31
	v_lshl_add_u64 v[228:229], s[64:65], 0, v[148:149]
	global_load_lds_dwordx4 v[226:227], off
	s_add_i32 m0, s31, 0x2000
	v_lshl_add_u64 v[230:231], s[28:29], 0, v[152:153]
	global_load_lds_dwordx4 v[228:229], off
	s_mov_b32 m0, s47
	v_lshl_add_u64 v[232:233], s[28:29], 0, v[150:151]
	global_load_lds_dwordx4 v[230:231], off
	s_mov_b32 m0, s48
	s_nop 0
	global_load_lds_dwordx4 v[232:233], off
	s_waitcnt vmcnt(8)
	s_waitcnt lgkmcnt(0)
	s_barrier
; #define PG8_STAGE(bufoff, gbase, voff) do { _Pragma("unroll") for (int _i = 0; _i < 2; ++_i) \
;         __builtin_amdgcn_global_load_lds((const unsigned*)((const char*)(gbase) + (voff)[_i]), (PG8_LAS unsigned*)(lds + (bufoff) + ldsw + _i * 8192), 16, 0, 0); } while (0)
; #define PG8_LDA(dst, b, h) do { _Pragma("unroll") for (int m = 0; m < 4; ++m) _Pragma("unroll") for (int k = 0; k < 2; ++k) dst[m][k] = *(const PG8_LAS bf16x8*)(lds + PG8_SA(b, h) + aoff + m * 2048 + k * 1024); } while (0)
; #define PG8_LDB(dst, b, h) do { _Pragma("unroll") for (int n = 0; n < 2; ++n) _Pragma("unroll") for (int k = 0; k < 2; ++k) dst[n][k] = *(const PG8_LAS bf16x8*)(lds + PG8_SB(b, h) + boff + n * 2048 + k * 1024); } while (0)
; #define PG8_MMA(ai, bj, At, Bt) do { __builtin_amdgcn_s_setprio(1); _Pragma("unroll") for (int m = 0; m < 4; ++m) _Pragma("unroll") for (int n = 0; n < 2; ++n) _Pragma("unroll") for (int k = 0; k < 2; ++k) \
;         acc[ai][bj][m][n] = __builtin_amdgcn_mfma_f32_16x16x32_bf16(Bt[n][k], At[m][k], acc[ai][bj][m][n], 0, 0, 0); __builtin_amdgcn_s_setprio(0); } while (0)
; #define PG8_WAIT_V(n) asm volatile("s_waitcnt vmcnt(" #n ")" ::: "memory")
; #define PG8_WAIT_L(n) asm volatile("s_waitcnt lgkmcnt(" #n ")" ::: "memory")
; #define PG8_BAR __builtin_amdgcn_s_barrier()
; #define PG8_SCHED __builtin_amdgcn_sched_barrier(0)
; template <class Epi, class Sched, bool ALIGN_EPI = false, bool SP2 = false>
; __device__ __forceinline__ void gemm_phase(PG8_LAS unsigned char* lds, const Gemm g, const Sched& S, const Epi& E) {
;     ...
;             PG8_WAIT_V(8); PG8_WAIT_L(0); PG8_BAR; PG8_MMA(0, 0, At, B0); PG8_MMA(0, 1, At, B1); PG8_BAR; PG8_SCHED;
;             PG8_LDA(At, 0, 1); PG8_STAGE(PG8_SB(0, 0), b2, voffB); PG8_STAGE(PG8_SB(0, 1), b2 + hstep, voffB); PG8_STAGE(PG8_SA(0, 0), a2, voffA);
;             PG8_WAIT_V(8); PG8_WAIT_L(0); PG8_BAR; PG8_MMA(1, 0, At, B0); PG8_MMA(1, 1, At, B1); PG8_BAR; PG8_SCHED;
;             PG8_LDB(B0, 1, 0); PG8_LDB(B1, 1, 1); PG8_SCHED; PG8_LDA(At, 1, 0); PG8_STAGE(PG8_SA(0, 1), a2 + hstep, voffA);
;             PG8_WAIT_V(8); PG8_WAIT_L(0); PG8_BAR; PG8_MMA(0, 0, At, B0); PG8_MMA(0, 1, At, B1); PG8_BAR; PG8_SCHED;
	s_setprio 1
	s_waitcnt lgkmcnt(0)
	v_mfma_f32_16x16x32_bf16 v[62:65], v[130:133], v[190:193], v[62:65]
	v_mfma_f32_16x16x32_bf16 v[58:61], v[138:141], v[190:193], v[58:61]
	v_mfma_f32_16x16x32_bf16 v[46:49], v[130:133], v[198:201], v[46:49]
	v_mfma_f32_16x16x32_bf16 v[42:45], v[138:141], v[198:201], v[42:45]
	v_mfma_f32_16x16x32_bf16 v[30:33], v[130:133], v[206:209], v[30:33]
	v_mfma_f32_16x16x32_bf16 v[26:29], v[138:141], v[206:209], v[26:29]
	v_mfma_f32_16x16x32_bf16 v[14:17], v[130:133], v[214:217], v[14:17]
	v_mfma_f32_16x16x32_bf16 v[10:13], v[138:141], v[214:217], v[10:13]
	v_mfma_f32_16x16x32_bf16 v[62:65], v[134:137], v[194:197], v[62:65]
	v_mfma_f32_16x16x32_bf16 v[58:61], v[142:145], v[194:197], v[58:61]
	v_mfma_f32_16x16x32_bf16 v[46:49], v[134:137], v[202:205], v[46:49]
	v_mfma_f32_16x16x32_bf16 v[42:45], v[142:145], v[202:205], v[42:45]
	v_mfma_f32_16x16x32_bf16 v[30:33], v[134:137], v[210:213], v[30:33]
	v_mfma_f32_16x16x32_bf16 v[26:29], v[142:145], v[210:213], v[26:29]
	v_mfma_f32_16x16x32_bf16 v[14:17], v[134:137], v[218:221], v[14:17]
	v_mfma_f32_16x16x32_bf16 v[10:13], v[142:145], v[218:221], v[10:13]
	s_setprio 0
	s_setprio 1
	v_mfma_f32_16x16x32_bf16 v[54:57], v[158:161], v[190:193], v[54:57]
	v_mfma_f32_16x16x32_bf16 v[50:53], v[182:185], v[190:193], v[50:53]
	v_mfma_f32_16x16x32_bf16 v[38:41], v[158:161], v[198:201], v[38:41]
	v_mfma_f32_16x16x32_bf16 v[34:37], v[182:185], v[198:201], v[34:37]
	v_mfma_f32_16x16x32_bf16 v[22:25], v[158:161], v[206:209], v[22:25]
	v_mfma_f32_16x16x32_bf16 v[18:21], v[182:185], v[206:209], v[18:21]
	v_mfma_f32_16x16x32_bf16 v[6:9], v[158:161], v[214:217], v[6:9]
	v_mfma_f32_16x16x32_bf16 v[2:5], v[182:185], v[214:217], v[2:5]
	v_mfma_f32_16x16x32_bf16 v[54:57], v[178:181], v[194:197], v[54:57]
	v_mfma_f32_16x16x32_bf16 v[50:53], v[186:189], v[194:197], v[50:53]
	v_mfma_f32_16x16x32_bf16 v[38:41], v[178:181], v[202:205], v[38:41]
	v_mfma_f32_16x16x32_bf16 v[34:37], v[186:189], v[202:205], v[34:37]
	v_mfma_f32_16x16x32_bf16 v[22:25], v[178:181], v[210:213], v[22:25]
	v_mfma_f32_16x16x32_bf16 v[18:21], v[186:189], v[210:213], v[18:21]
	v_mfma_f32_16x16x32_bf16 v[6:9], v[178:181], v[218:221], v[6:9]
	v_mfma_f32_16x16x32_bf16 v[2:5], v[186:189], v[218:221], v[2:5]
	s_setprio 0
	s_barrier
	s_add_i32 s31, 0, 0x18000
	s_add_i32 s63, 0, 0x1c000
	v_add_u32_e32 v142, s31, v174
	v_add_u32_e32 v186, s63, v174
	ds_read_b128 v[130:133], v142
	ds_read_b128 v[134:137], v142 offset:1024
	ds_read_b128 v[138:141], v142 offset:2048
	ds_read_b128 v[142:145], v142 offset:3072
	ds_read_b128 v[158:161], v186
	ds_read_b128 v[178:181], v186 offset:1024
	ds_read_b128 v[182:185], v186 offset:2048
	ds_read_b128 v[186:189], v186 offset:3072
	s_add_u32 s28, s28, s10
	s_addc_u32 s29, s29, s11
	s_mov_b32 m0, s49
	v_lshl_add_u64 v[234:235], s[28:29], 0, v[152:153]
	ds_read_b128 v[190:193], v177 offset:32768
	ds_read_b128 v[194:197], v177 offset:33792
	ds_read_b128 v[198:201], v177 offset:34816
	ds_read_b128 v[202:205], v177 offset:35840
	ds_read_b128 v[206:209], v177 offset:36864
	ds_read_b128 v[210:213], v177 offset:37888
	ds_read_b128 v[214:217], v177 offset:38912
	ds_read_b128 v[218:221], v177 offset:39936
	global_load_lds_dwordx4 v[234:235], off
	v_lshl_add_u64 v[234:235], s[28:29], 0, v[150:151]
	s_mov_b32 m0, s50
	s_nop 0
	global_load_lds_dwordx4 v[234:235], off
	s_waitcnt vmcnt(8)
	s_waitcnt lgkmcnt(0)
	s_barrier
	s_setprio 1
	s_waitcnt lgkmcnt(0)
	v_mfma_f32_16x16x32_bf16 v[126:129], v[130:133], v[190:193], v[126:129]
	v_mfma_f32_16x16x32_bf16 v[122:125], v[138:141], v[190:193], v[122:125]
	v_mfma_f32_16x16x32_bf16 v[110:113], v[130:133], v[198:201], v[110:113]
	v_mfma_f32_16x16x32_bf16 v[106:109], v[138:141], v[198:201], v[106:109]
	v_mfma_f32_16x16x32_bf16 v[94:97], v[130:133], v[206:209], v[94:97]
	v_mfma_f32_16x16x32_bf16 v[90:93], v[138:141], v[206:209], v[90:93]
	v_mfma_f32_16x16x32_bf16 v[78:81], v[130:133], v[214:217], v[78:81]
	v_mfma_f32_16x16x32_bf16 v[74:77], v[138:141], v[214:217], v[74:77]
	v_mfma_f32_16x16x32_bf16 v[126:129], v[134:137], v[194:197], v[126:129]
	v_mfma_f32_16x16x32_bf16 v[122:125], v[142:145], v[194:197], v[122:125]
	v_mfma_f32_16x16x32_bf16 v[110:113], v[134:137], v[202:205], v[110:113]
	v_mfma_f32_16x16x32_bf16 v[106:109], v[142:145], v[202:205], v[106:109]
	v_mfma_f32_16x16x32_bf16 v[94:97], v[134:137], v[210:213], v[94:97]
	v_mfma_f32_16x16x32_bf16 v[90:93], v[142:145], v[210:213], v[90:93]
	v_mfma_f32_16x16x32_bf16 v[78:81], v[134:137], v[218:221], v[78:81]
	v_mfma_f32_16x16x32_bf16 v[74:77], v[142:145], v[218:221], v[74:77]
	s_setprio 0
	s_setprio 1
	v_mfma_f32_16x16x32_bf16 v[118:121], v[158:161], v[190:193], v[118:121]
	v_mfma_f32_16x16x32_bf16 v[114:117], v[182:185], v[190:193], v[114:117]
	v_mfma_f32_16x16x32_bf16 v[102:105], v[158:161], v[198:201], v[102:105]
	v_mfma_f32_16x16x32_bf16 v[98:101], v[182:185], v[198:201], v[98:101]
	v_mfma_f32_16x16x32_bf16 v[86:89], v[158:161], v[206:209], v[86:89]
	v_mfma_f32_16x16x32_bf16 v[82:85], v[182:185], v[206:209], v[82:85]
	v_mfma_f32_16x16x32_bf16 v[70:73], v[158:161], v[214:217], v[70:73]
	v_mfma_f32_16x16x32_bf16 v[66:69], v[182:185], v[214:217], v[66:69]
	v_mfma_f32_16x16x32_bf16 v[118:121], v[178:181], v[194:197], v[118:121]
	v_mfma_f32_16x16x32_bf16 v[114:117], v[186:189], v[194:197], v[114:117]
	v_mfma_f32_16x16x32_bf16 v[102:105], v[178:181], v[202:205], v[102:105]
	v_mfma_f32_16x16x32_bf16 v[98:101], v[186:189], v[202:205], v[98:101]
	v_mfma_f32_16x16x32_bf16 v[86:89], v[178:181], v[210:213], v[86:89]
	v_mfma_f32_16x16x32_bf16 v[82:85], v[186:189], v[210:213], v[82:85]
	v_mfma_f32_16x16x32_bf16 v[70:73], v[178:181], v[218:221], v[70:73]
	v_mfma_f32_16x16x32_bf16 v[66:69], v[186:189], v[218:221], v[66:69]
	s_setprio 0
	s_barrier
; #define PG8_STAGE(bufoff, gbase, voff) do { _Pragma("unroll") for (int _i = 0; _i < 2; ++_i) \
;         __builtin_amdgcn_global_load_lds((const unsigned*)((const char*)(gbase) + (voff)[_i]), (PG8_LAS unsigned*)(lds + (bufoff) + ldsw + _i * 8192), 16, 0, 0); } while (0)
; #define PG8_LDA(dst, b, h) do { _Pragma("unroll") for (int m = 0; m < 4; ++m) _Pragma("unroll") for (int k = 0; k < 2; ++k) dst[m][k] = *(const PG8_LAS bf16x8*)(lds + PG8_SA(b, h) + aoff + m * 2048 + k * 1024); } while (0)
; #define PG8_MMA(ai, bj, At, Bt) do { __builtin_amdgcn_s_setprio(1); _Pragma("unroll") for (int m = 0; m < 4; ++m) _Pragma("unroll") for (int n = 0; n < 2; ++n) _Pragma("unroll") for (int k = 0; k < 2; ++k) \
;         acc[ai][bj][m][n] = __builtin_amdgcn_mfma_f32_16x16x32_bf16(Bt[n][k], At[m][k], acc[ai][bj][m][n], 0, 0, 0); __builtin_amdgcn_s_setprio(0); } while (0)
; #define PG8_WAIT_V(n) asm volatile("s_waitcnt vmcnt(" #n ")" ::: "memory")
; #define PG8_WAIT_L(n) asm volatile("s_waitcnt lgkmcnt(" #n ")" ::: "memory")
; #define PG8_BAR __builtin_amdgcn_s_barrier()
; #define PG8_SCHED __builtin_amdgcn_sched_barrier(0)
; template <class Epi, class Sched, bool ALIGN_EPI = false, bool SP2 = false>
; __device__ __forceinline__ void gemm_phase(PG8_LAS unsigned char* lds, const Gemm g, const Sched& S, const Epi& E) {
;     ...
;         for (int t = 0; t < nt; t += 2) {
;     ...
;             PG8_LDA(At, 1, 1); PG8_STAGE(PG8_SB(1, 0), b3, voffB); PG8_STAGE(PG8_SB(1, 1), b3 + hstep, voffB); PG8_STAGE(PG8_SA(1, 0), a3, voffA);
;             PG8_WAIT_V(8); PG8_WAIT_L(0); PG8_BAR; PG8_MMA(1, 0, At, B0); PG8_MMA(1, 1, At, B1); PG8_BAR; PG8_SCHED;
	s_add_i32 s28, s31, s36
	v_lshl_add_u64 v[222:223], v[222:223], 0, s[80:81]
	s_mov_b32 m0, s28
	ds_read_b128 v[190:193], v177 offset:49152
	ds_read_b128 v[194:197], v177 offset:50176
	ds_read_b128 v[198:201], v177 offset:51200
	ds_read_b128 v[202:205], v177 offset:52224
	ds_read_b128 v[206:209], v177 offset:53248
	ds_read_b128 v[210:213], v177 offset:54272
	ds_read_b128 v[214:217], v177 offset:55296
	ds_read_b128 v[218:221], v177 offset:56320
	global_load_lds_dwordx4 v[222:223], off
	v_lshl_add_u64 v[222:223], v[224:225], 0, s[80:81]
	s_add_i32 m0, s28, 0x2000
	s_add_i32 s28, s63, s36
	global_load_lds_dwordx4 v[222:223], off
	v_lshl_add_u64 v[222:223], v[226:227], 0, s[80:81]
	s_mov_b32 m0, s28
	s_nop 0
	global_load_lds_dwordx4 v[222:223], off
	v_lshl_add_u64 v[222:223], v[228:229], 0, s[80:81]
	s_add_i32 m0, s28, 0x2000
	s_nop 0
	global_load_lds_dwordx4 v[222:223], off
	v_lshl_add_u64 v[222:223], v[230:231], 0, s[80:81]
	s_mov_b32 m0, s52
	s_nop 0
	global_load_lds_dwordx4 v[222:223], off
	v_lshl_add_u64 v[222:223], v[232:233], 0, s[80:81]
	s_mov_b32 m0, s53
	s_nop 0
	global_load_lds_dwordx4 v[222:223], off
	s_waitcnt vmcnt(8)
	s_waitcnt lgkmcnt(0)
	s_barrier
	s_setprio 1
	s_waitcnt lgkmcnt(0)
	v_mfma_f32_16x16x32_bf16 v[62:65], v[130:133], v[190:193], v[62:65]
	v_mfma_f32_16x16x32_bf16 v[58:61], v[138:141], v[190:193], v[58:61]
	v_mfma_f32_16x16x32_bf16 v[46:49], v[130:133], v[198:201], v[46:49]
	v_mfma_f32_16x16x32_bf16 v[42:45], v[138:141], v[198:201], v[42:45]
	v_mfma_f32_16x16x32_bf16 v[30:33], v[130:133], v[206:209], v[30:33]
	v_mfma_f32_16x16x32_bf16 v[26:29], v[138:141], v[206:209], v[26:29]
	v_mfma_f32_16x16x32_bf16 v[14:17], v[130:133], v[214:217], v[14:17]
	v_mfma_f32_16x16x32_bf16 v[10:13], v[138:141], v[214:217], v[10:13]
	v_mfma_f32_16x16x32_bf16 v[62:65], v[134:137], v[194:197], v[62:65]
	v_mfma_f32_16x16x32_bf16 v[58:61], v[142:145], v[194:197], v[58:61]
	v_mfma_f32_16x16x32_bf16 v[46:49], v[134:137], v[202:205], v[46:49]
	v_mfma_f32_16x16x32_bf16 v[42:45], v[142:145], v[202:205], v[42:45]
	v_mfma_f32_16x16x32_bf16 v[30:33], v[134:137], v[210:213], v[30:33]
	v_mfma_f32_16x16x32_bf16 v[26:29], v[142:145], v[210:213], v[26:29]
	v_mfma_f32_16x16x32_bf16 v[14:17], v[134:137], v[218:221], v[14:17]
	v_mfma_f32_16x16x32_bf16 v[10:13], v[142:145], v[218:221], v[10:13]
	s_setprio 0
	s_setprio 1
	v_mfma_f32_16x16x32_bf16 v[54:57], v[158:161], v[190:193], v[54:57]
	v_mfma_f32_16x16x32_bf16 v[50:53], v[182:185], v[190:193], v[50:53]
	v_mfma_f32_16x16x32_bf16 v[38:41], v[158:161], v[198:201], v[38:41]
	v_mfma_f32_16x16x32_bf16 v[34:37], v[182:185], v[198:201], v[34:37]
	v_mfma_f32_16x16x32_bf16 v[22:25], v[158:161], v[206:209], v[22:25]
	v_mfma_f32_16x16x32_bf16 v[18:21], v[182:185], v[206:209], v[18:21]
	v_mfma_f32_16x16x32_bf16 v[6:9], v[158:161], v[214:217], v[6:9]
	v_mfma_f32_16x16x32_bf16 v[2:5], v[182:185], v[214:217], v[2:5]
	v_mfma_f32_16x16x32_bf16 v[54:57], v[178:181], v[194:197], v[54:57]
	v_mfma_f32_16x16x32_bf16 v[50:53], v[186:189], v[194:197], v[50:53]
	v_mfma_f32_16x16x32_bf16 v[38:41], v[178:181], v[202:205], v[38:41]
	v_mfma_f32_16x16x32_bf16 v[34:37], v[186:189], v[202:205], v[34:37]
	v_mfma_f32_16x16x32_bf16 v[22:25], v[178:181], v[210:213], v[22:25]
	v_mfma_f32_16x16x32_bf16 v[18:21], v[186:189], v[210:213], v[18:21]
	v_mfma_f32_16x16x32_bf16 v[6:9], v[178:181], v[218:221], v[6:9]
	v_mfma_f32_16x16x32_bf16 v[2:5], v[186:189], v[218:221], v[2:5]
	s_setprio 0
	s_add_u32 s61, s61, 0x100
	s_addc_u32 s62, s62, 0
	s_add_u32 s2, s2, 0x100
	s_addc_u32 s3, s3, 0
	s_cmp_ge_i32 s30, s51
	s_mov_b32 s28, s30
	s_barrier
	s_cbranch_scc0 .LBB0_190
	s_mov_b32 s63, 0xc000
	s_movk_i32 s64, 0x90
	s_movk_i32 s65, 0x1e00

; #define PG8_STAGE(bufoff, gbase, voff) do { _Pragma("unroll") for (int _i = 0; _i < 2; ++_i) \
;         __builtin_amdgcn_global_load_lds((const unsigned*)((const char*)(gbase) + (voff)[_i]), (PG8_LAS unsigned*)(lds + (bufoff) + ldsw + _i * 8192), 16, 0, 0); } while (0)
; #define PG8_LDA(dst, b, h) do { _Pragma("unroll") for (int m = 0; m < 4; ++m) _Pragma("unroll") for (int k = 0; k < 2; ++k) dst[m][k] = *(const PG8_LAS bf16x8*)(lds + PG8_SA(b, h) + aoff + m * 2048 + k * 1024); } while (0)
; #define PG8_LDB(dst, b, h) do { _Pragma("unroll") for (int n = 0; n < 2; ++n) _Pragma("unroll") for (int k = 0; k < 2; ++k) dst[n][k] = *(const PG8_LAS bf16x8*)(lds + PG8_SB(b, h) + boff + n * 2048 + k * 1024); } while (0)
; #define PG8_MMA(ai, bj, At, Bt) do { __builtin_amdgcn_s_setprio(1); _Pragma("unroll") for (int m = 0; m < 4; ++m) _Pragma("unroll") for (int n = 0; n < 2; ++n) _Pragma("unroll") for (int k = 0; k < 2; ++k) \
;         acc[ai][bj][m][n] = __builtin_amdgcn_mfma_f32_16x16x32_bf16(Bt[n][k], At[m][k], acc[ai][bj][m][n], 0, 0, 0); __builtin_amdgcn_s_setprio(0); } while (0)
; #define PG8_WAIT_V(n) asm volatile("s_waitcnt vmcnt(" #n ")" ::: "memory")
; #define PG8_WAIT_L(n) asm volatile("s_waitcnt lgkmcnt(" #n ")" ::: "memory")
; #define PG8_BAR __builtin_amdgcn_s_barrier()
; #define PG8_SCHED __builtin_amdgcn_sched_barrier(0)
; template <class Epi, class Sched, bool ALIGN_EPI = false, bool SP2 = false>
; __device__ __forceinline__ void gemm_phase(PG8_LAS unsigned char* lds, const Gemm g, const Sched& S, const Epi& E) {
;     ...
;             const bool last = (t == nt - 2);
;             const char* a1 = cA + (size_t)(t + 1) * kstep;
;             const char* a2 = last ? nA : cA + (size_t)(t + 2) * kstep; const char* b2 = last ? nB : cB + (size_t)(t + 2) * kstep;
;             const char* a3 = a2 + kstep; const char* b3 = b2 + kstep;
;             if (last && has_next) S.a_ready(nxt);
;             if constexpr (SP2) {
;             PG8_LDB(B0, 0, 0); PG8_LDB(B1, 0, 1); PG8_SCHED; PG8_LDA(At, 0, 0); PG8_STAGE(PG8_SA(1, 1), a1 + hstep, voffA);
;             PG8_WAIT_V(8); PG8_WAIT_L(0); PG8_BAR; PG8_MMA(0, 0, At, B0); PG8_MMA(0, 1, At, B1); PG8_BAR; PG8_SCHED;
;             PG8_LDA(At, 0, 1); PG8_STAGE(PG8_SB(0, 0), b2, voffB); PG8_STAGE(PG8_SB(0, 1), b2 + hstep, voffB); PG8_STAGE(PG8_SA(0, 0), a2, voffA);
.LBB0_745:
	s_add_i32 s30, s28, 2
	s_add_u32 s31, s0, 0x80
	s_addc_u32 s29, s1, 0
	s_add_i32 s66, 0, 0x10000
	s_cmp_eq_u32 s50, s28
	s_cselect_b32 s29, s25, s29
	s_cselect_b32 s28, s24, s31
	s_cselect_b32 s65, s27, s63
	s_cselect_b32 s64, s26, s62
	s_add_i32 s31, 0, 0x14000
	v_add_u32_e32 v50, s66, v174
	v_add_u32_e32 v177, s31, v174
	ds_read_b128 v[26:29], v50
	ds_read_b128 v[38:41], v50 offset:1024
	ds_read_b128 v[42:45], v50 offset:2048
	ds_read_b128 v[50:53], v50 offset:3072
	ds_read_b128 v[158:161], v177
	ds_read_b128 v[178:181], v177 offset:1024
	ds_read_b128 v[182:185], v177 offset:2048
	ds_read_b128 v[186:189], v177 offset:3072
	v_lshl_add_u64 v[222:223], s[0:1], 0, v[156:157]
	s_add_i32 m0, s42, 0xc000
	ds_read_b128 v[190:193], v176
	ds_read_b128 v[194:197], v176 offset:1024
	ds_read_b128 v[198:201], v176 offset:2048
	ds_read_b128 v[202:205], v176 offset:3072
	ds_read_b128 v[206:209], v176 offset:4096
	ds_read_b128 v[210:213], v176 offset:5120
	ds_read_b128 v[214:217], v176 offset:6144
	ds_read_b128 v[218:221], v176 offset:7168
	global_load_lds_dwordx4 v[222:223], off
	v_lshl_add_u64 v[222:223], s[0:1], 0, v[154:155]
	s_add_i32 m0, s42, 0xe000
	s_nop 0
	global_load_lds_dwordx4 v[222:223], off
	s_waitcnt vmcnt(8)
	s_waitcnt lgkmcnt(0)
	s_barrier
	s_setprio 1
	s_waitcnt lgkmcnt(0)
	v_mfma_f32_16x16x32_bf16 v[142:145], v[26:29], v[190:193], v[142:145]
	v_mfma_f32_16x16x32_bf16 v[138:141], v[42:45], v[190:193], v[138:141]
	v_mfma_f32_16x16x32_bf16 v[126:129], v[26:29], v[198:201], v[126:129]
	v_mfma_f32_16x16x32_bf16 v[122:125], v[42:45], v[198:201], v[122:125]
	v_mfma_f32_16x16x32_bf16 v[110:113], v[26:29], v[206:209], v[110:113]
	v_mfma_f32_16x16x32_bf16 v[106:109], v[42:45], v[206:209], v[106:109]
	v_mfma_f32_16x16x32_bf16 v[94:97], v[26:29], v[214:217], v[94:97]
	v_mfma_f32_16x16x32_bf16 v[90:93], v[42:45], v[214:217], v[90:93]
	v_mfma_f32_16x16x32_bf16 v[142:145], v[38:41], v[194:197], v[142:145]
	v_mfma_f32_16x16x32_bf16 v[138:141], v[50:53], v[194:197], v[138:141]
	v_mfma_f32_16x16x32_bf16 v[126:129], v[38:41], v[202:205], v[126:129]
	v_mfma_f32_16x16x32_bf16 v[122:125], v[50:53], v[202:205], v[122:125]
	v_mfma_f32_16x16x32_bf16 v[110:113], v[38:41], v[210:213], v[110:113]
	v_mfma_f32_16x16x32_bf16 v[106:109], v[50:53], v[210:213], v[106:109]
	v_mfma_f32_16x16x32_bf16 v[94:97], v[38:41], v[218:221], v[94:97]
	v_mfma_f32_16x16x32_bf16 v[90:93], v[50:53], v[218:221], v[90:93]
	s_setprio 0
	s_setprio 1
	v_mfma_f32_16x16x32_bf16 v[134:137], v[158:161], v[190:193], v[134:137]
	v_mfma_f32_16x16x32_bf16 v[130:133], v[182:185], v[190:193], v[130:133]
	v_mfma_f32_16x16x32_bf16 v[118:121], v[158:161], v[198:201], v[118:121]
	v_mfma_f32_16x16x32_bf16 v[114:117], v[182:185], v[198:201], v[114:117]
	v_mfma_f32_16x16x32_bf16 v[102:105], v[158:161], v[206:209], v[102:105]
	v_mfma_f32_16x16x32_bf16 v[98:101], v[182:185], v[206:209], v[98:101]
	v_mfma_f32_16x16x32_bf16 v[86:89], v[158:161], v[214:217], v[86:89]
	v_mfma_f32_16x16x32_bf16 v[82:85], v[182:185], v[214:217], v[82:85]
	v_mfma_f32_16x16x32_bf16 v[134:137], v[178:181], v[194:197], v[134:137]
	v_mfma_f32_16x16x32_bf16 v[130:133], v[186:189], v[194:197], v[130:133]
	v_mfma_f32_16x16x32_bf16 v[118:121], v[178:181], v[202:205], v[118:121]
	v_mfma_f32_16x16x32_bf16 v[114:117], v[186:189], v[202:205], v[114:117]
	v_mfma_f32_16x16x32_bf16 v[102:105], v[178:181], v[210:213], v[102:105]
	v_mfma_f32_16x16x32_bf16 v[98:101], v[186:189], v[210:213], v[98:101]
	v_mfma_f32_16x16x32_bf16 v[86:89], v[178:181], v[218:221], v[86:89]
	v_mfma_f32_16x16x32_bf16 v[82:85], v[186:189], v[218:221], v[82:85]
	s_setprio 0
	s_barrier
	s_add_i32 s66, s66, s37
	v_lshl_add_u64 v[222:223], s[64:65], 0, v[0:1]
	s_mov_b32 m0, s66
	ds_read_b128 v[190:193], v176 offset:16384
	ds_read_b128 v[194:197], v176 offset:17408
	ds_read_b128 v[198:201], v176 offset:18432
	ds_read_b128 v[202:205], v176 offset:19456
	ds_read_b128 v[206:209], v176 offset:20480
	ds_read_b128 v[210:213], v176 offset:21504
	ds_read_b128 v[214:217], v176 offset:22528
	ds_read_b128 v[218:221], v176 offset:23552
	global_load_lds_dwordx4 v[222:223], off
	s_add_i32 m0, s66, 0x2000
	v_lshl_add_u64 v[224:225], s[64:65], 0, v[152:153]
	s_add_u32 s64, s64, s8
	s_addc_u32 s65, s65, s9
	s_add_i32 s31, s31, s37
	global_load_lds_dwordx4 v[224:225], off
	v_lshl_add_u64 v[226:227], s[64:65], 0, v[0:1]
	s_mov_b32 m0, s31
	v_lshl_add_u64 v[228:229], s[64:65], 0, v[152:153]
	global_load_lds_dwordx4 v[226:227], off
	s_add_i32 m0, s31, 0x2000
	v_lshl_add_u64 v[230:231], s[28:29], 0, v[148:149]
	global_load_lds_dwordx4 v[228:229], off
	s_mov_b32 m0, s42
	v_lshl_add_u64 v[232:233], s[28:29], 0, v[150:151]
	global_load_lds_dwordx4 v[230:231], off
	s_mov_b32 m0, s43
	s_nop 0
	global_load_lds_dwordx4 v[232:233], off
	s_waitcnt vmcnt(8)
	s_waitcnt lgkmcnt(0)
	s_barrier
; #define PG8_STAGE(bufoff, gbase, voff) do { _Pragma("unroll") for (int _i = 0; _i < 2; ++_i) \
;         __builtin_amdgcn_global_load_lds((const unsigned*)((const char*)(gbase) + (voff)[_i]), (PG8_LAS unsigned*)(lds + (bufoff) + ldsw + _i * 8192), 16, 0, 0); } while (0)
; #define PG8_LDA(dst, b, h) do { _Pragma("unroll") for (int m = 0; m < 4; ++m) _Pragma("unroll") for (int k = 0; k < 2; ++k) dst[m][k] = *(const PG8_LAS bf16x8*)(lds + PG8_SA(b, h) + aoff + m * 2048 + k * 1024); } while (0)
; #define PG8_LDB(dst, b, h) do { _Pragma("unroll") for (int n = 0; n < 2; ++n) _Pragma("unroll") for (int k = 0; k < 2; ++k) dst[n][k] = *(const PG8_LAS bf16x8*)(lds + PG8_SB(b, h) + boff + n * 2048 + k * 1024); } while (0)
; #define PG8_MMA(ai, bj, At, Bt) do { __builtin_amdgcn_s_setprio(1); _Pragma("unroll") for (int m = 0; m < 4; ++m) _Pragma("unroll") for (int n = 0; n < 2; ++n) _Pragma("unroll") for (int k = 0; k < 2; ++k) \
;         acc[ai][bj][m][n] = __builtin_amdgcn_mfma_f32_16x16x32_bf16(Bt[n][k], At[m][k], acc[ai][bj][m][n], 0, 0, 0); __builtin_amdgcn_s_setprio(0); } while (0)
; #define PG8_WAIT_V(n) asm volatile("s_waitcnt vmcnt(" #n ")" ::: "memory")
; #define PG8_WAIT_L(n) asm volatile("s_waitcnt lgkmcnt(" #n ")" ::: "memory")
; #define PG8_BAR __builtin_amdgcn_s_barrier()
; #define PG8_SCHED __builtin_amdgcn_sched_barrier(0)
; template <class Epi, class Sched, bool ALIGN_EPI = false, bool SP2 = false>
; __device__ __forceinline__ void gemm_phase(PG8_LAS unsigned char* lds, const Gemm g, const Sched& S, const Epi& E) {
;     ...
;             PG8_WAIT_V(8); PG8_WAIT_L(0); PG8_BAR; PG8_MMA(1, 0, At, B0); PG8_MMA(1, 1, At, B1); PG8_BAR; PG8_SCHED;
;             PG8_LDB(B0, 1, 0); PG8_LDB(B1, 1, 1); PG8_SCHED; PG8_LDA(At, 1, 0); PG8_STAGE(PG8_SA(0, 1), a2 + hstep, voffA);
;             PG8_WAIT_V(8); PG8_WAIT_L(0); PG8_BAR; PG8_MMA(0, 0, At, B0); PG8_MMA(0, 1, At, B1); PG8_BAR; PG8_SCHED;
	s_setprio 1
	s_waitcnt lgkmcnt(0)
	v_mfma_f32_16x16x32_bf16 v[78:81], v[26:29], v[190:193], v[78:81]
	v_mfma_f32_16x16x32_bf16 v[74:77], v[42:45], v[190:193], v[74:77]
	v_mfma_f32_16x16x32_bf16 v[62:65], v[26:29], v[198:201], v[62:65]
	v_mfma_f32_16x16x32_bf16 v[58:61], v[42:45], v[198:201], v[58:61]
	v_mfma_f32_16x16x32_bf16 v[34:37], v[26:29], v[206:209], v[34:37]
	v_mfma_f32_16x16x32_bf16 v[30:33], v[42:45], v[206:209], v[30:33]
	v_mfma_f32_16x16x32_bf16 v[14:17], v[26:29], v[214:217], v[14:17]
	v_mfma_f32_16x16x32_bf16 v[10:13], v[42:45], v[214:217], v[10:13]
	v_mfma_f32_16x16x32_bf16 v[78:81], v[38:41], v[194:197], v[78:81]
	v_mfma_f32_16x16x32_bf16 v[74:77], v[50:53], v[194:197], v[74:77]
	v_mfma_f32_16x16x32_bf16 v[62:65], v[38:41], v[202:205], v[62:65]
	v_mfma_f32_16x16x32_bf16 v[58:61], v[50:53], v[202:205], v[58:61]
	v_mfma_f32_16x16x32_bf16 v[34:37], v[38:41], v[210:213], v[34:37]
	v_mfma_f32_16x16x32_bf16 v[30:33], v[50:53], v[210:213], v[30:33]
	v_mfma_f32_16x16x32_bf16 v[14:17], v[38:41], v[218:221], v[14:17]
	v_mfma_f32_16x16x32_bf16 v[10:13], v[50:53], v[218:221], v[10:13]
	s_setprio 0
	s_setprio 1
	v_mfma_f32_16x16x32_bf16 v[46:49], v[182:185], v[198:201], v[46:49]
	v_mfma_f32_16x16x32_bf16 v[22:25], v[158:161], v[206:209], v[22:25]
	v_mfma_f32_16x16x32_bf16 v[18:21], v[182:185], v[206:209], v[18:21]
	v_mfma_f32_16x16x32_bf16 v[6:9], v[158:161], v[214:217], v[6:9]
	v_mfma_f32_16x16x32_bf16 v[2:5], v[182:185], v[214:217], v[2:5]
	v_mfma_f32_16x16x32_bf16 v[26:29], v[158:161], v[190:193], v[70:73]
	v_mfma_f32_16x16x32_bf16 v[38:41], v[182:185], v[190:193], v[66:69]
	v_mfma_f32_16x16x32_bf16 v[42:45], v[158:161], v[198:201], v[54:57]
	v_mfma_f32_16x16x32_bf16 v[46:49], v[186:189], v[202:205], v[46:49]
	v_mfma_f32_16x16x32_bf16 v[22:25], v[178:181], v[210:213], v[22:25]
	v_mfma_f32_16x16x32_bf16 v[18:21], v[186:189], v[210:213], v[18:21]
	v_mfma_f32_16x16x32_bf16 v[6:9], v[178:181], v[218:221], v[6:9]
	v_mfma_f32_16x16x32_bf16 v[2:5], v[186:189], v[218:221], v[2:5]
	v_mfma_f32_16x16x32_bf16 v[26:29], v[178:181], v[194:197], v[26:29]
	v_mfma_f32_16x16x32_bf16 v[38:41], v[186:189], v[194:197], v[38:41]
	v_mfma_f32_16x16x32_bf16 v[42:45], v[178:181], v[202:205], v[42:45]
	s_setprio 0
	s_barrier
	s_add_i32 s31, 0, 0x18000
	s_add_i32 s64, 0, 0x1c000
	v_add_u32_e32 v70, s31, v174
	v_add_u32_e32 v177, s64, v174
	ds_read_b128 v[50:53], v70
	ds_read_b128 v[54:57], v70 offset:1024
	ds_read_b128 v[66:69], v70 offset:2048
	ds_read_b128 v[70:73], v70 offset:3072
	ds_read_b128 v[158:161], v177
	ds_read_b128 v[178:181], v177 offset:1024
	ds_read_b128 v[182:185], v177 offset:2048
	ds_read_b128 v[186:189], v177 offset:3072
	s_add_u32 s28, s28, s8
	s_addc_u32 s29, s29, s9
	s_mov_b32 m0, s44
	v_lshl_add_u64 v[234:235], s[28:29], 0, v[148:149]
	ds_read_b128 v[190:193], v176 offset:32768
	ds_read_b128 v[194:197], v176 offset:33792
	ds_read_b128 v[198:201], v176 offset:34816
	ds_read_b128 v[202:205], v176 offset:35840
	ds_read_b128 v[206:209], v176 offset:36864
	ds_read_b128 v[210:213], v176 offset:37888
	ds_read_b128 v[214:217], v176 offset:38912
	ds_read_b128 v[218:221], v176 offset:39936
	global_load_lds_dwordx4 v[234:235], off
	v_lshl_add_u64 v[234:235], s[28:29], 0, v[150:151]
	s_mov_b32 m0, s45
	s_nop 0
	global_load_lds_dwordx4 v[234:235], off
	s_waitcnt vmcnt(8)
	s_waitcnt lgkmcnt(0)
	s_barrier
	s_setprio 1
	s_waitcnt lgkmcnt(0)
	v_mfma_f32_16x16x32_bf16 v[142:145], v[50:53], v[190:193], v[142:145]
	v_mfma_f32_16x16x32_bf16 v[138:141], v[66:69], v[190:193], v[138:141]
	v_mfma_f32_16x16x32_bf16 v[126:129], v[50:53], v[198:201], v[126:129]
	v_mfma_f32_16x16x32_bf16 v[122:125], v[66:69], v[198:201], v[122:125]
	v_mfma_f32_16x16x32_bf16 v[110:113], v[50:53], v[206:209], v[110:113]
	v_mfma_f32_16x16x32_bf16 v[106:109], v[66:69], v[206:209], v[106:109]
	v_mfma_f32_16x16x32_bf16 v[94:97], v[50:53], v[214:217], v[94:97]
	v_mfma_f32_16x16x32_bf16 v[90:93], v[66:69], v[214:217], v[90:93]
	v_mfma_f32_16x16x32_bf16 v[142:145], v[54:57], v[194:197], v[142:145]
	v_mfma_f32_16x16x32_bf16 v[138:141], v[70:73], v[194:197], v[138:141]
	v_mfma_f32_16x16x32_bf16 v[126:129], v[54:57], v[202:205], v[126:129]
	v_mfma_f32_16x16x32_bf16 v[122:125], v[70:73], v[202:205], v[122:125]
	v_mfma_f32_16x16x32_bf16 v[110:113], v[54:57], v[210:213], v[110:113]
	v_mfma_f32_16x16x32_bf16 v[106:109], v[70:73], v[210:213], v[106:109]
	v_mfma_f32_16x16x32_bf16 v[94:97], v[54:57], v[218:221], v[94:97]
	v_mfma_f32_16x16x32_bf16 v[90:93], v[70:73], v[218:221], v[90:93]
	s_setprio 0
	s_setprio 1
	v_mfma_f32_16x16x32_bf16 v[134:137], v[158:161], v[190:193], v[134:137]
	v_mfma_f32_16x16x32_bf16 v[130:133], v[182:185], v[190:193], v[130:133]
	v_mfma_f32_16x16x32_bf16 v[118:121], v[158:161], v[198:201], v[118:121]
	v_mfma_f32_16x16x32_bf16 v[114:117], v[182:185], v[198:201], v[114:117]
	v_mfma_f32_16x16x32_bf16 v[102:105], v[158:161], v[206:209], v[102:105]
	v_mfma_f32_16x16x32_bf16 v[98:101], v[182:185], v[206:209], v[98:101]
	v_mfma_f32_16x16x32_bf16 v[86:89], v[158:161], v[214:217], v[86:89]
	v_mfma_f32_16x16x32_bf16 v[82:85], v[182:185], v[214:217], v[82:85]
	v_mfma_f32_16x16x32_bf16 v[134:137], v[178:181], v[194:197], v[134:137]
	v_mfma_f32_16x16x32_bf16 v[130:133], v[186:189], v[194:197], v[130:133]
	v_mfma_f32_16x16x32_bf16 v[118:121], v[178:181], v[202:205], v[118:121]
	v_mfma_f32_16x16x32_bf16 v[114:117], v[186:189], v[202:205], v[114:117]
	v_mfma_f32_16x16x32_bf16 v[102:105], v[178:181], v[210:213], v[102:105]
	v_mfma_f32_16x16x32_bf16 v[98:101], v[186:189], v[210:213], v[98:101]
	v_mfma_f32_16x16x32_bf16 v[86:89], v[178:181], v[218:221], v[86:89]
	v_mfma_f32_16x16x32_bf16 v[82:85], v[186:189], v[218:221], v[82:85]
	s_setprio 0
	s_barrier
; #define PG8_STAGE(bufoff, gbase, voff) do { _Pragma("unroll") for (int _i = 0; _i < 2; ++_i) \
;         __builtin_amdgcn_global_load_lds((const unsigned*)((const char*)(gbase) + (voff)[_i]), (PG8_LAS unsigned*)(lds + (bufoff) + ldsw + _i * 8192), 16, 0, 0); } while (0)
; #define PG8_LDA(dst, b, h) do { _Pragma("unroll") for (int m = 0; m < 4; ++m) _Pragma("unroll") for (int k = 0; k < 2; ++k) dst[m][k] = *(const PG8_LAS bf16x8*)(lds + PG8_SA(b, h) + aoff + m * 2048 + k * 1024); } while (0)
; #define PG8_MMA(ai, bj, At, Bt) do { __builtin_amdgcn_s_setprio(1); _Pragma("unroll") for (int m = 0; m < 4; ++m) _Pragma("unroll") for (int n = 0; n < 2; ++n) _Pragma("unroll") for (int k = 0; k < 2; ++k) \
;         acc[ai][bj][m][n] = __builtin_amdgcn_mfma_f32_16x16x32_bf16(Bt[n][k], At[m][k], acc[ai][bj][m][n], 0, 0, 0); __builtin_amdgcn_s_setprio(0); } while (0)
; #define PG8_WAIT_V(n) asm volatile("s_waitcnt vmcnt(" #n ")" ::: "memory")
; #define PG8_WAIT_L(n) asm volatile("s_waitcnt lgkmcnt(" #n ")" ::: "memory")
; #define PG8_BAR __builtin_amdgcn_s_barrier()
; #define PG8_SCHED __builtin_amdgcn_sched_barrier(0)
; template <class Epi, class Sched, bool ALIGN_EPI = false, bool SP2 = false>
; __device__ __forceinline__ void gemm_phase(PG8_LAS unsigned char* lds, const Gemm g, const Sched& S, const Epi& E) {
;     ...
;         for (int t = 0; t < nt; t += 2) {
;             const bool last = (t == nt - 2);
;             const char* a1 = cA + (size_t)(t + 1) * kstep;
;             const char* a2 = last ? nA : cA + (size_t)(t + 2) * kstep; const char* b2 = last ? nB : cB + (size_t)(t + 2) * kstep;
;             const char* a3 = a2 + kstep; const char* b3 = b2 + kstep;
;     ...
;             PG8_LDA(At, 1, 1); PG8_STAGE(PG8_SB(1, 0), b3, voffB); PG8_STAGE(PG8_SB(1, 1), b3 + hstep, voffB); PG8_STAGE(PG8_SA(1, 0), a3, voffA);
;             PG8_WAIT_V(8); PG8_WAIT_L(0); PG8_BAR; PG8_MMA(1, 0, At, B0); PG8_MMA(1, 1, At, B1); PG8_BAR; PG8_SCHED;
	s_add_i32 s28, s31, s37
	v_lshl_add_u64 v[222:223], v[222:223], 0, s[80:81]
	s_mov_b32 m0, s28
	ds_read_b128 v[190:193], v176 offset:49152
	ds_read_b128 v[194:197], v176 offset:50176
	ds_read_b128 v[198:201], v176 offset:51200
	ds_read_b128 v[202:205], v176 offset:52224
	ds_read_b128 v[206:209], v176 offset:53248
	ds_read_b128 v[210:213], v176 offset:54272
	ds_read_b128 v[214:217], v176 offset:55296
	ds_read_b128 v[218:221], v176 offset:56320
	global_load_lds_dwordx4 v[222:223], off
	v_lshl_add_u64 v[222:223], v[224:225], 0, s[80:81]
	s_add_i32 m0, s28, 0x2000
	s_add_i32 s28, s64, s37
	global_load_lds_dwordx4 v[222:223], off
	v_lshl_add_u64 v[222:223], v[226:227], 0, s[80:81]
	s_mov_b32 m0, s28
	s_nop 0
	global_load_lds_dwordx4 v[222:223], off
	v_lshl_add_u64 v[222:223], v[228:229], 0, s[80:81]
	s_add_i32 m0, s28, 0x2000
	s_nop 0
	global_load_lds_dwordx4 v[222:223], off
	v_lshl_add_u64 v[222:223], v[230:231], 0, s[80:81]
	s_mov_b32 m0, s48
	s_nop 0
	global_load_lds_dwordx4 v[222:223], off
	v_lshl_add_u64 v[222:223], v[232:233], 0, s[80:81]
	s_mov_b32 m0, s49
	s_nop 0
	global_load_lds_dwordx4 v[222:223], off
	s_waitcnt vmcnt(8)
	s_waitcnt lgkmcnt(0)
	s_barrier
	s_setprio 1
	s_waitcnt lgkmcnt(0)
	v_mfma_f32_16x16x32_bf16 v[78:81], v[50:53], v[190:193], v[78:81]
	v_mfma_f32_16x16x32_bf16 v[74:77], v[66:69], v[190:193], v[74:77]
	v_mfma_f32_16x16x32_bf16 v[62:65], v[50:53], v[198:201], v[62:65]
	v_mfma_f32_16x16x32_bf16 v[58:61], v[66:69], v[198:201], v[58:61]
	v_mfma_f32_16x16x32_bf16 v[34:37], v[50:53], v[206:209], v[34:37]
	v_mfma_f32_16x16x32_bf16 v[30:33], v[66:69], v[206:209], v[30:33]
	v_mfma_f32_16x16x32_bf16 v[14:17], v[50:53], v[214:217], v[14:17]
	v_mfma_f32_16x16x32_bf16 v[10:13], v[66:69], v[214:217], v[10:13]
	v_mfma_f32_16x16x32_bf16 v[78:81], v[54:57], v[194:197], v[78:81]
	v_mfma_f32_16x16x32_bf16 v[74:77], v[70:73], v[194:197], v[74:77]
	v_mfma_f32_16x16x32_bf16 v[62:65], v[54:57], v[202:205], v[62:65]
	v_mfma_f32_16x16x32_bf16 v[58:61], v[70:73], v[202:205], v[58:61]
	v_mfma_f32_16x16x32_bf16 v[34:37], v[54:57], v[210:213], v[34:37]
	v_mfma_f32_16x16x32_bf16 v[30:33], v[70:73], v[210:213], v[30:33]
	v_mfma_f32_16x16x32_bf16 v[14:17], v[54:57], v[218:221], v[14:17]
	v_mfma_f32_16x16x32_bf16 v[10:13], v[70:73], v[218:221], v[10:13]
	s_setprio 0
	s_setprio 1
	v_mfma_f32_16x16x32_bf16 v[26:29], v[158:161], v[190:193], v[26:29]
	v_mfma_f32_16x16x32_bf16 v[70:73], v[178:181], v[194:197], v[26:29]
	v_mfma_f32_16x16x32_bf16 v[26:29], v[182:185], v[190:193], v[38:41]
	v_mfma_f32_16x16x32_bf16 v[66:69], v[186:189], v[194:197], v[26:29]
	v_mfma_f32_16x16x32_bf16 v[26:29], v[158:161], v[198:201], v[42:45]
	v_mfma_f32_16x16x32_bf16 v[54:57], v[178:181], v[202:205], v[26:29]
	v_mfma_f32_16x16x32_bf16 v[26:29], v[182:185], v[198:201], v[46:49]
	v_mfma_f32_16x16x32_bf16 v[22:25], v[158:161], v[206:209], v[22:25]
	v_mfma_f32_16x16x32_bf16 v[18:21], v[182:185], v[206:209], v[18:21]
	v_mfma_f32_16x16x32_bf16 v[6:9], v[158:161], v[214:217], v[6:9]
	v_mfma_f32_16x16x32_bf16 v[2:5], v[182:185], v[214:217], v[2:5]
	v_mfma_f32_16x16x32_bf16 v[46:49], v[186:189], v[202:205], v[26:29]
	v_mfma_f32_16x16x32_bf16 v[22:25], v[178:181], v[210:213], v[22:25]
	v_mfma_f32_16x16x32_bf16 v[18:21], v[186:189], v[210:213], v[18:21]
	v_mfma_f32_16x16x32_bf16 v[6:9], v[178:181], v[218:221], v[6:9]
	v_mfma_f32_16x16x32_bf16 v[2:5], v[186:189], v[218:221], v[2:5]
	s_setprio 0
	s_add_u32 s62, s62, 0x100
	s_addc_u32 s63, s63, 0
	s_add_u32 s0, s0, 0x100
	s_addc_u32 s1, s1, 0
	s_cmp_ge_i32 s30, s47
	s_mov_b32 s28, s30
	s_barrier
	s_cbranch_scc0 .LBB0_745
	s_mov_b32 s66, 0x1c000
	s_mov_b32 s63, 0xc000
	s_movk_i32 s64, 0x90
	s_movk_i32 s65, 0x1e00
